# attention QK/PV blocks: ring-buffered ds_read prefetch (8-10 deep) instead of lgkmcnt(0) serialization in NSA sel/win and MLA loops
# speedup vs baseline: 1.0244x; 1.0244x over previous
; #define LAS __attribute__((address_space(3)))
; __device__ __forceinline__ f32x16 mfma32(bf16x8 a, bf16x8 b, f32x16 c) { return __builtin_amdgcn_mfma_f32_32x32x16_bf16(a, b, c, 0, 0, 0); }
; template <int DQK, bool STATS, bool PRE, class Src, class Mask, class Post> ...
;     ...
;         if (!STATS && act) {
;             const int vb = (i & 1) * VBUF;
; #pragma unroll
;             for (int g16 = 0; g16 < 4; ++g16) {
;                 const bf16x8 pf = __builtin_bit_cast(bf16x8, pk[g16]);
; #pragma unroll
;                 for (int blk = 0; blk < 4; ++blk) {
;                     const bf16x8 vf = *(const LAS bf16x8*)(lv + vb + (blk * 32 + c) * VS_ + g16 * 32 + h * 16);
;                     a.o[blk] = mfma32(vf, pf, a.o[blk]);
;                 }
;             }
.LBB0_1790:
	s_or_b64 exec, exec, s[22:23]
	s_and_b64 vcc, exec, s[12:13]
	s_cbranch_vccnz .LBB0_1796
	s_bitcmp1_b32 s55, 0
	s_cselect_b32 s12, 0x4800, 0
	v_add_u32_e32 v0, s12, v206
	ds_read_b128 v[210:213], v0 offset:34816
	ds_read_b128 v[214:217], v0 offset:39424
	ds_read_b128 v[218:221], v0 offset:44032
	ds_read_b128 v[222:225], v0 offset:48640
	ds_read_b128 v[226:229], v0 offset:34848
	ds_read_b128 v[230:233], v0 offset:39456
	ds_read_b128 v[234:237], v0 offset:44064
	ds_read_b128 v[238:241], v0 offset:48672
	s_waitcnt lgkmcnt(7)
	v_mfma_f32_32x32x16_bf16 v[80:95], v[210:213], v[2:5], v[80:95]
	ds_read_b128 v[210:213], v0 offset:34880
	s_waitcnt lgkmcnt(7)
	v_mfma_f32_32x32x16_bf16 v[48:63], v[214:217], v[2:5], v[48:63]
	ds_read_b128 v[214:217], v0 offset:39488
	s_waitcnt lgkmcnt(7)
	v_mfma_f32_32x32x16_bf16 v[32:47], v[218:221], v[2:5], v[32:47]
	ds_read_b128 v[218:221], v0 offset:44096
	s_waitcnt lgkmcnt(7)
	v_mfma_f32_32x32x16_bf16 v[16:31], v[222:225], v[2:5], v[16:31]
	ds_read_b128 v[222:225], v0 offset:48704
	s_waitcnt lgkmcnt(7)
	v_mfma_f32_32x32x16_bf16 v[80:95], v[226:229], v[10:13], v[80:95]
	ds_read_b128 v[226:229], v0 offset:34912
	s_waitcnt lgkmcnt(7)
	v_mfma_f32_32x32x16_bf16 v[48:63], v[230:233], v[10:13], v[48:63]
	ds_read_b128 v[230:233], v0 offset:39520
	s_waitcnt lgkmcnt(7)
	v_mfma_f32_32x32x16_bf16 v[32:47], v[234:237], v[10:13], v[32:47]
	ds_read_b128 v[234:237], v0 offset:44128
	s_waitcnt lgkmcnt(7)
	v_mfma_f32_32x32x16_bf16 v[16:31], v[238:241], v[10:13], v[16:31]
	ds_read_b128 v[238:241], v0 offset:48736
	s_waitcnt lgkmcnt(7)
	v_mfma_f32_32x32x16_bf16 v[80:95], v[210:213], v[6:9], v[80:95]
	s_waitcnt lgkmcnt(6)
	v_mfma_f32_32x32x16_bf16 v[48:63], v[214:217], v[6:9], v[48:63]
	s_waitcnt lgkmcnt(5)
	v_mfma_f32_32x32x16_bf16 v[32:47], v[218:221], v[6:9], v[32:47]
	s_waitcnt lgkmcnt(4)
	v_mfma_f32_32x32x16_bf16 v[16:31], v[222:225], v[6:9], v[16:31]
	s_waitcnt lgkmcnt(3)
	v_mfma_f32_32x32x16_bf16 v[80:95], v[226:229], v[144:147], v[80:95]
	s_waitcnt lgkmcnt(2)
	v_mfma_f32_32x32x16_bf16 v[48:63], v[230:233], v[144:147], v[48:63]
	s_waitcnt lgkmcnt(1)
	v_mfma_f32_32x32x16_bf16 v[32:47], v[234:237], v[144:147], v[32:47]
	s_waitcnt lgkmcnt(0)
	v_mfma_f32_32x32x16_bf16 v[16:31], v[238:241], v[144:147], v[16:31]
	s_add_i32 s22, s55, 1
	s_cmp_ge_u32 s22, s36
	s_mov_b64 s[90:91], 0
	s_cbranch_scc0 .LBB0_1797

.LBB0_1797:
	s_lshr_b32 s12, s22, 3
	s_and_b32 s12, s12, 0x1ffffffc
	v_add_u32_e32 v0, s12, v180
	ds_read_b32 v0, v0
	s_and_b32 s12, s22, 31
	s_waitcnt lgkmcnt(0)
	v_lshrrev_b32_e32 v14, s22, v0
	v_bfe_u32 v0, v0, s12, 1
	v_and_b32_e32 v14, 1, v14
	v_cmp_ne_u32_e32 vcc, 0, v0
	v_cmp_eq_u32_e64 s[88:89], 1, v14
	s_cbranch_vccz .LBB0_1803
	s_bitcmp0_b32 s55, 0
	s_mov_b64 s[12:13], -1
	s_cbranch_scc1 .LBB0_1800
	s_mov_b64 s[12:13], 0
	ds_read_b128 v[210:213], v207
	ds_read_b128 v[214:217], v207 offset:8704
	ds_read_b128 v[218:221], v207 offset:32
	ds_read_b128 v[222:225], v207 offset:8736
	ds_read_b128 v[226:229], v207 offset:64
	ds_read_b128 v[230:233], v207 offset:8768
	ds_read_b128 v[234:237], v207 offset:96
	ds_read_b128 v[238:241], v207 offset:8800
	s_waitcnt lgkmcnt(7)
	v_mfma_f32_32x32x16_bf16 v[64:79], v[210:213], v[112:115], 0
	ds_read_b128 v[210:213], v207 offset:128
	s_waitcnt lgkmcnt(7)
	v_mfma_f32_32x32x16_bf16 v[96:111], v[214:217], v[112:115], 0
	ds_read_b128 v[214:217], v207 offset:8832
	s_waitcnt lgkmcnt(7)
	v_mfma_f32_32x32x16_bf16 v[64:79], v[218:221], v[116:119], v[64:79]
	ds_read_b128 v[218:221], v207 offset:160
	s_waitcnt lgkmcnt(7)
	v_mfma_f32_32x32x16_bf16 v[96:111], v[222:225], v[116:119], v[96:111]
	ds_read_b128 v[222:225], v207 offset:8864
	s_waitcnt lgkmcnt(7)
	v_mfma_f32_32x32x16_bf16 v[64:79], v[226:229], v[120:123], v[64:79]
	ds_read_b128 v[226:229], v207 offset:192
	s_waitcnt lgkmcnt(7)
	v_mfma_f32_32x32x16_bf16 v[96:111], v[230:233], v[120:123], v[96:111]
	ds_read_b128 v[230:233], v207 offset:8896
	s_waitcnt lgkmcnt(7)
	v_mfma_f32_32x32x16_bf16 v[64:79], v[234:237], v[124:127], v[64:79]
	ds_read_b128 v[234:237], v207 offset:224
	s_waitcnt lgkmcnt(7)
	v_mfma_f32_32x32x16_bf16 v[96:111], v[238:241], v[124:127], v[96:111]
	ds_read_b128 v[238:241], v207 offset:8928
	s_waitcnt lgkmcnt(7)
	v_mfma_f32_32x32x16_bf16 v[64:79], v[210:213], v[128:131], v[64:79]
	s_waitcnt lgkmcnt(6)
	v_mfma_f32_32x32x16_bf16 v[96:111], v[214:217], v[128:131], v[96:111]
	s_waitcnt lgkmcnt(5)
	v_mfma_f32_32x32x16_bf16 v[64:79], v[218:221], v[132:135], v[64:79]
	s_waitcnt lgkmcnt(4)
	v_mfma_f32_32x32x16_bf16 v[96:111], v[222:225], v[132:135], v[96:111]
	s_waitcnt lgkmcnt(3)
	v_mfma_f32_32x32x16_bf16 v[64:79], v[226:229], v[136:139], v[64:79]
	s_waitcnt lgkmcnt(2)
	v_mfma_f32_32x32x16_bf16 v[96:111], v[230:233], v[136:139], v[96:111]
	s_waitcnt lgkmcnt(1)
	v_mfma_f32_32x32x16_bf16 v[64:79], v[234:237], v[140:143], v[64:79]
	s_waitcnt lgkmcnt(0)
	v_mfma_f32_32x32x16_bf16 v[96:111], v[238:241], v[140:143], v[96:111]
.LBB0_1800:
	s_andn2_b64 vcc, exec, s[12:13]
	s_cbranch_vccnz .LBB0_1802
	ds_read_b128 v[210:213], v207 offset:17408
	ds_read_b128 v[214:217], v207 offset:26112
	ds_read_b128 v[218:221], v207 offset:17440
	ds_read_b128 v[222:225], v207 offset:26144
	ds_read_b128 v[226:229], v207 offset:17472
	ds_read_b128 v[230:233], v207 offset:26176
	ds_read_b128 v[234:237], v207 offset:17504
	ds_read_b128 v[238:241], v207 offset:26208
	s_waitcnt lgkmcnt(7)
	v_mfma_f32_32x32x16_bf16 v[64:79], v[210:213], v[112:115], 0
	ds_read_b128 v[210:213], v207 offset:17536
	s_waitcnt lgkmcnt(7)
	v_mfma_f32_32x32x16_bf16 v[96:111], v[214:217], v[112:115], 0
	ds_read_b128 v[214:217], v207 offset:26240
	s_waitcnt lgkmcnt(7)
	v_mfma_f32_32x32x16_bf16 v[64:79], v[218:221], v[116:119], v[64:79]
	ds_read_b128 v[218:221], v207 offset:17568
	s_waitcnt lgkmcnt(7)
	v_mfma_f32_32x32x16_bf16 v[96:111], v[222:225], v[116:119], v[96:111]
	ds_read_b128 v[222:225], v207 offset:26272
	s_waitcnt lgkmcnt(7)
	v_mfma_f32_32x32x16_bf16 v[64:79], v[226:229], v[120:123], v[64:79]
	ds_read_b128 v[226:229], v207 offset:17600
	s_waitcnt lgkmcnt(7)
	v_mfma_f32_32x32x16_bf16 v[96:111], v[230:233], v[120:123], v[96:111]
	ds_read_b128 v[230:233], v207 offset:26304
	s_waitcnt lgkmcnt(7)
	v_mfma_f32_32x32x16_bf16 v[64:79], v[234:237], v[124:127], v[64:79]
	ds_read_b128 v[234:237], v207 offset:17632
	s_waitcnt lgkmcnt(7)
	v_mfma_f32_32x32x16_bf16 v[96:111], v[238:241], v[124:127], v[96:111]
	ds_read_b128 v[238:241], v207 offset:26336
	s_waitcnt lgkmcnt(7)
	v_mfma_f32_32x32x16_bf16 v[64:79], v[210:213], v[128:131], v[64:79]
	s_waitcnt lgkmcnt(6)
	v_mfma_f32_32x32x16_bf16 v[96:111], v[214:217], v[128:131], v[96:111]
	s_waitcnt lgkmcnt(5)
	v_mfma_f32_32x32x16_bf16 v[64:79], v[218:221], v[132:135], v[64:79]
	s_waitcnt lgkmcnt(4)
	v_mfma_f32_32x32x16_bf16 v[96:111], v[222:225], v[132:135], v[96:111]
	s_waitcnt lgkmcnt(3)
	v_mfma_f32_32x32x16_bf16 v[64:79], v[226:229], v[136:139], v[64:79]
	s_waitcnt lgkmcnt(2)
	v_mfma_f32_32x32x16_bf16 v[96:111], v[230:233], v[136:139], v[96:111]
	s_waitcnt lgkmcnt(1)
	v_mfma_f32_32x32x16_bf16 v[64:79], v[234:237], v[140:143], v[64:79]
	s_waitcnt lgkmcnt(0)
	v_mfma_f32_32x32x16_bf16 v[96:111], v[238:241], v[140:143], v[96:111]

; #define LAS __attribute__((address_space(3)))
; __device__ __forceinline__ f32x16 mfma32(bf16x8 a, bf16x8 b, f32x16 c) { return __builtin_amdgcn_mfma_f32_32x32x16_bf16(a, b, c, 0, 0, 0); }
;     __device__ __forceinline__ bool begin(int t) { kb_ = t * 64; on = (selw[t >> 5] >> (t & 31)) & 1u; return __ballot(on) != 0ull; }
; template <int DQK, bool STATS, bool PRE, class Src, class Mask, class Post> ...
;     ...
;         if (!STATS && act) {
;             const int vb = (i & 1) * VBUF;
; #pragma unroll
;             for (int g16 = 0; g16 < 4; ++g16) {
;                 const bf16x8 pf = __builtin_bit_cast(bf16x8, pk[g16]);
; #pragma unroll
;                 for (int blk = 0; blk < 4; ++blk) {
;                     const bf16x8 vf = *(const LAS bf16x8*)(lv + vb + (blk * 32 + c) * VS_ + g16 * 32 + h * 16);
;                     a.o[blk] = mfma32(vf, pf, a.o[blk]);
;                 }
;             }
;             __builtin_amdgcn_sched_group_barrier(0x100, 6, 0);
; #pragma unroll
;             for (int z = 0; z < 10; ++z) { __builtin_amdgcn_sched_group_barrier(0x008, 1, 0); __builtin_amdgcn_sched_group_barrier(0x100, 1, 0); }
;             __builtin_amdgcn_sched_group_barrier(0x008, 6, 0);
;         }
;         bool actn = false;
;         if (t + 1 < te) { actn = mask.begin(t + 1); if (actn) { if ((i + 1) & 1) ATT_QK(1); else ATT_QK(0); } }
.LBB0_1879:
	s_or_b64 exec, exec, s[24:25]
	s_and_b64 vcc, exec, s[22:23]
	s_cbranch_vccnz .LBB0_1881
	s_bitcmp1_b32 s54, 0
	s_cselect_b32 s22, 0x4800, 0
	v_add_u32_e32 v0, s22, v222
	ds_read_b128 v[224:227], v0 offset:34816
	ds_read_b128 v[228:231], v0 offset:39424
	ds_read_b128 v[232:235], v0 offset:44032
	ds_read_b128 v[236:239], v0 offset:48640
	ds_read_b128 v[240:243], v0 offset:34848
	ds_read_b128 v[244:247], v0 offset:39456
	s_waitcnt lgkmcnt(5)
	v_mfma_f32_32x32x16_bf16 v[80:95], v[224:227], v[2:5], v[80:95]
	ds_read_b128 v[224:227], v0 offset:44064
	s_waitcnt lgkmcnt(5)
	v_mfma_f32_32x32x16_bf16 v[48:63], v[228:231], v[2:5], v[48:63]
	ds_read_b128 v[228:231], v0 offset:48672
	s_waitcnt lgkmcnt(5)
	v_mfma_f32_32x32x16_bf16 v[32:47], v[232:235], v[2:5], v[32:47]
	ds_read_b128 v[232:235], v0 offset:34880
	s_waitcnt lgkmcnt(5)
	v_mfma_f32_32x32x16_bf16 v[16:31], v[236:239], v[2:5], v[16:31]
	ds_read_b128 v[236:239], v0 offset:39488
	s_waitcnt lgkmcnt(5)
	v_mfma_f32_32x32x16_bf16 v[80:95], v[240:243], v[10:13], v[80:95]
	ds_read_b128 v[240:243], v0 offset:44096
	s_waitcnt lgkmcnt(5)
	v_mfma_f32_32x32x16_bf16 v[48:63], v[244:247], v[10:13], v[48:63]
	ds_read_b128 v[244:247], v0 offset:48704
	s_waitcnt lgkmcnt(5)
	v_mfma_f32_32x32x16_bf16 v[32:47], v[224:227], v[10:13], v[32:47]
	ds_read_b128 v[224:227], v0 offset:34912
	s_waitcnt lgkmcnt(5)
	v_mfma_f32_32x32x16_bf16 v[16:31], v[228:231], v[10:13], v[16:31]
	ds_read_b128 v[228:231], v0 offset:39520
	s_waitcnt lgkmcnt(5)
	v_mfma_f32_32x32x16_bf16 v[80:95], v[232:235], v[6:9], v[80:95]
	ds_read_b128 v[232:235], v0 offset:44128
	s_waitcnt lgkmcnt(5)
	v_mfma_f32_32x32x16_bf16 v[48:63], v[236:239], v[6:9], v[48:63]
	ds_read_b128 v[236:239], v0 offset:48736
	s_waitcnt lgkmcnt(5)
	v_mfma_f32_32x32x16_bf16 v[32:47], v[240:243], v[6:9], v[32:47]
	s_waitcnt lgkmcnt(4)
	v_mfma_f32_32x32x16_bf16 v[16:31], v[244:247], v[6:9], v[16:31]
	s_waitcnt lgkmcnt(3)
	v_mfma_f32_32x32x16_bf16 v[80:95], v[224:227], v[144:147], v[80:95]
	s_waitcnt lgkmcnt(2)
	v_mfma_f32_32x32x16_bf16 v[48:63], v[228:231], v[144:147], v[48:63]
	s_waitcnt lgkmcnt(1)
	v_mfma_f32_32x32x16_bf16 v[32:47], v[232:235], v[144:147], v[32:47]
	s_waitcnt lgkmcnt(0)
	v_mfma_f32_32x32x16_bf16 v[16:31], v[236:239], v[144:147], v[16:31]
.LBB0_1881:
	s_add_i32 s22, s38, s54
	s_add_i32 s22, s22, 1
	s_cmp_lt_i32 s22, s36
	s_cselect_b64 s[24:25], -1, 0
	s_cmp_ge_i32 s22, s36
	s_cbranch_scc1 .LBB0_1887
	s_bitcmp0_b32 s54, 0
	s_mov_b64 s[22:23], -1
	s_cbranch_scc1 .LBB0_1884
	s_mov_b64 s[22:23], 0
	ds_read_b128 v[224:227], v170
	ds_read_b128 v[228:231], v170 offset:8704
	ds_read_b128 v[232:235], v170 offset:32
	ds_read_b128 v[236:239], v170 offset:8736
	ds_read_b128 v[240:243], v170 offset:64
	ds_read_b128 v[244:247], v170 offset:8768
	s_waitcnt lgkmcnt(5)
	v_mfma_f32_32x32x16_bf16 v[64:79], v[224:227], v[112:115], 0
	ds_read_b128 v[224:227], v170 offset:96
	s_waitcnt lgkmcnt(5)
	v_mfma_f32_32x32x16_bf16 v[96:111], v[228:231], v[112:115], 0
	ds_read_b128 v[228:231], v170 offset:8800
	s_waitcnt lgkmcnt(5)
	v_mfma_f32_32x32x16_bf16 v[64:79], v[232:235], v[116:119], v[64:79]
	ds_read_b128 v[232:235], v170 offset:128
	s_waitcnt lgkmcnt(5)
	v_mfma_f32_32x32x16_bf16 v[96:111], v[236:239], v[116:119], v[96:111]
	ds_read_b128 v[236:239], v170 offset:8832
	s_waitcnt lgkmcnt(5)
	v_mfma_f32_32x32x16_bf16 v[64:79], v[240:243], v[120:123], v[64:79]
	ds_read_b128 v[240:243], v170 offset:160
	s_waitcnt lgkmcnt(5)
	v_mfma_f32_32x32x16_bf16 v[96:111], v[244:247], v[120:123], v[96:111]
	ds_read_b128 v[244:247], v170 offset:8864
	s_waitcnt lgkmcnt(5)
	v_mfma_f32_32x32x16_bf16 v[64:79], v[224:227], v[124:127], v[64:79]
	ds_read_b128 v[224:227], v170 offset:192
	s_waitcnt lgkmcnt(5)
	v_mfma_f32_32x32x16_bf16 v[96:111], v[228:231], v[124:127], v[96:111]
	ds_read_b128 v[228:231], v170 offset:8896
	s_waitcnt lgkmcnt(5)
	v_mfma_f32_32x32x16_bf16 v[64:79], v[232:235], v[128:131], v[64:79]
	ds_read_b128 v[232:235], v170 offset:224
	s_waitcnt lgkmcnt(5)
	v_mfma_f32_32x32x16_bf16 v[96:111], v[236:239], v[128:131], v[96:111]
	ds_read_b128 v[236:239], v170 offset:8928
	s_waitcnt lgkmcnt(5)
	v_mfma_f32_32x32x16_bf16 v[64:79], v[240:243], v[132:135], v[64:79]
	s_waitcnt lgkmcnt(4)
	v_mfma_f32_32x32x16_bf16 v[96:111], v[244:247], v[132:135], v[96:111]
	s_waitcnt lgkmcnt(3)
	v_mfma_f32_32x32x16_bf16 v[64:79], v[224:227], v[136:139], v[64:79]
	s_waitcnt lgkmcnt(2)
	v_mfma_f32_32x32x16_bf16 v[96:111], v[228:231], v[136:139], v[96:111]
	s_waitcnt lgkmcnt(1)
	v_mfma_f32_32x32x16_bf16 v[64:79], v[232:235], v[140:143], v[64:79]
	s_waitcnt lgkmcnt(0)
	v_mfma_f32_32x32x16_bf16 v[96:111], v[236:239], v[140:143], v[96:111]
.LBB0_1884:
	s_andn2_b64 vcc, exec, s[22:23]
	s_cbranch_vccnz .LBB0_1886
	ds_read_b128 v[224:227], v170 offset:17408
	ds_read_b128 v[228:231], v170 offset:26112
	ds_read_b128 v[232:235], v170 offset:17440
	ds_read_b128 v[236:239], v170 offset:26144
	ds_read_b128 v[240:243], v170 offset:17472
	ds_read_b128 v[244:247], v170 offset:26176
	s_waitcnt lgkmcnt(5)
	v_mfma_f32_32x32x16_bf16 v[64:79], v[224:227], v[112:115], 0
	ds_read_b128 v[224:227], v170 offset:17504
	s_waitcnt lgkmcnt(5)
	v_mfma_f32_32x32x16_bf16 v[96:111], v[228:231], v[112:115], 0
	ds_read_b128 v[228:231], v170 offset:26208
	s_waitcnt lgkmcnt(5)
	v_mfma_f32_32x32x16_bf16 v[64:79], v[232:235], v[116:119], v[64:79]
	ds_read_b128 v[232:235], v170 offset:17536
	s_waitcnt lgkmcnt(5)
	v_mfma_f32_32x32x16_bf16 v[96:111], v[236:239], v[116:119], v[96:111]
	ds_read_b128 v[236:239], v170 offset:26240
	s_waitcnt lgkmcnt(5)
	v_mfma_f32_32x32x16_bf16 v[64:79], v[240:243], v[120:123], v[64:79]
	ds_read_b128 v[240:243], v170 offset:17568
	s_waitcnt lgkmcnt(5)
	v_mfma_f32_32x32x16_bf16 v[96:111], v[244:247], v[120:123], v[96:111]
	ds_read_b128 v[244:247], v170 offset:26272
	s_waitcnt lgkmcnt(5)
	v_mfma_f32_32x32x16_bf16 v[64:79], v[224:227], v[124:127], v[64:79]
	ds_read_b128 v[224:227], v170 offset:17600
	s_waitcnt lgkmcnt(5)
	v_mfma_f32_32x32x16_bf16 v[96:111], v[228:231], v[124:127], v[96:111]
	ds_read_b128 v[228:231], v170 offset:26304
	s_waitcnt lgkmcnt(5)
	v_mfma_f32_32x32x16_bf16 v[64:79], v[232:235], v[128:131], v[64:79]
	ds_read_b128 v[232:235], v170 offset:17632
	s_waitcnt lgkmcnt(5)
	v_mfma_f32_32x32x16_bf16 v[96:111], v[236:239], v[128:131], v[96:111]
	ds_read_b128 v[236:239], v170 offset:26336
	s_waitcnt lgkmcnt(5)
	v_mfma_f32_32x32x16_bf16 v[64:79], v[240:243], v[132:135], v[64:79]
	s_waitcnt lgkmcnt(4)
	v_mfma_f32_32x32x16_bf16 v[96:111], v[244:247], v[132:135], v[96:111]
	s_waitcnt lgkmcnt(3)
	v_mfma_f32_32x32x16_bf16 v[64:79], v[224:227], v[136:139], v[64:79]
	s_waitcnt lgkmcnt(2)
	v_mfma_f32_32x32x16_bf16 v[96:111], v[228:231], v[136:139], v[96:111]
	s_waitcnt lgkmcnt(1)
	v_mfma_f32_32x32x16_bf16 v[64:79], v[232:235], v[140:143], v[64:79]
	s_waitcnt lgkmcnt(0)
	v_mfma_f32_32x32x16_bf16 v[96:111], v[236:239], v[140:143], v[96:111]

.LBB0_2878:
	s_or_b64 exec, exec, s[64:65]
	s_add_i32 s66, s89, 1
	s_cmp_ge_u32 s66, s50
	s_mov_b64 s[62:63], 0
	s_cbranch_scc1 .LBB0_2886
	v_cmp_le_i32_e32 vcc, s87, v163
	s_and_saveexec_b64 s[64:65], vcc
	s_cbranch_execz .LBB0_2885
	s_bitcmp0_b32 s89, 0
	s_mov_b64 s[62:63], -1
	s_cbranch_scc1 .LBB0_2882
	s_mov_b64 s[62:63], 0
	ds_read_b128 v[208:211], v205
	ds_read_b128 v[212:215], v205 offset:12800
	ds_read_b128 v[216:219], v205 offset:32
	ds_read_b128 v[220:223], v205 offset:12832
	ds_read_b128 v[224:227], v205 offset:64
	ds_read_b128 v[228:231], v205 offset:12864
	ds_read_b128 v[232:235], v205 offset:96
	ds_read_b128 v[236:239], v205 offset:12896
	ds_read_b128 v[240:243], v205 offset:128
	ds_read_b128 v[244:247], v205 offset:12928
	s_waitcnt lgkmcnt(9)
	v_mfma_f32_32x32x16_bf16 v[2:17], v[208:211], v[98:101], 0
	ds_read_b128 v[208:211], v205 offset:160
	s_waitcnt lgkmcnt(9)
	v_mfma_f32_32x32x16_bf16 v[82:97], v[212:215], v[98:101], 0
	ds_read_b128 v[212:215], v205 offset:12960
	s_waitcnt lgkmcnt(9)
	v_mfma_f32_32x32x16_bf16 v[2:17], v[216:219], v[102:105], v[2:17]
	ds_read_b128 v[216:219], v205 offset:192
	s_waitcnt lgkmcnt(9)
	v_mfma_f32_32x32x16_bf16 v[82:97], v[220:223], v[102:105], v[82:97]
	ds_read_b128 v[220:223], v205 offset:12992
	s_waitcnt lgkmcnt(9)
	v_mfma_f32_32x32x16_bf16 v[2:17], v[224:227], v[106:109], v[2:17]
	ds_read_b128 v[224:227], v205 offset:224
	s_waitcnt lgkmcnt(9)
	v_mfma_f32_32x32x16_bf16 v[82:97], v[228:231], v[106:109], v[82:97]
	ds_read_b128 v[228:231], v205 offset:13024
	s_waitcnt lgkmcnt(9)
	v_mfma_f32_32x32x16_bf16 v[2:17], v[232:235], v[110:113], v[2:17]
	ds_read_b128 v[232:235], v205 offset:256
	s_waitcnt lgkmcnt(9)
	v_mfma_f32_32x32x16_bf16 v[82:97], v[236:239], v[110:113], v[82:97]
	ds_read_b128 v[236:239], v205 offset:13056
	s_waitcnt lgkmcnt(9)
	v_mfma_f32_32x32x16_bf16 v[2:17], v[240:243], v[114:117], v[2:17]
	ds_read_b128 v[240:243], v205 offset:288
	s_waitcnt lgkmcnt(9)
	v_mfma_f32_32x32x16_bf16 v[82:97], v[244:247], v[114:117], v[82:97]
	ds_read_b128 v[244:247], v205 offset:13088
	s_waitcnt lgkmcnt(9)
	v_mfma_f32_32x32x16_bf16 v[2:17], v[208:211], v[118:121], v[2:17]
	ds_read_b128 v[208:211], v205 offset:320
	s_waitcnt lgkmcnt(9)
	v_mfma_f32_32x32x16_bf16 v[82:97], v[212:215], v[118:121], v[82:97]
	ds_read_b128 v[212:215], v205 offset:13120
	s_waitcnt lgkmcnt(9)
	v_mfma_f32_32x32x16_bf16 v[2:17], v[216:219], v[122:125], v[2:17]
	ds_read_b128 v[216:219], v205 offset:352
	s_waitcnt lgkmcnt(9)
	v_mfma_f32_32x32x16_bf16 v[82:97], v[220:223], v[122:125], v[82:97]
	ds_read_b128 v[220:223], v205 offset:13152
	s_waitcnt lgkmcnt(9)
	v_mfma_f32_32x32x16_bf16 v[2:17], v[224:227], v[126:129], v[2:17]
	s_waitcnt lgkmcnt(8)
	v_mfma_f32_32x32x16_bf16 v[82:97], v[228:231], v[126:129], v[82:97]
	s_waitcnt lgkmcnt(7)
	v_mfma_f32_32x32x16_bf16 v[2:17], v[232:235], v[130:133], v[2:17]
	s_waitcnt lgkmcnt(6)
	v_mfma_f32_32x32x16_bf16 v[82:97], v[236:239], v[130:133], v[82:97]
	s_waitcnt lgkmcnt(5)
	v_mfma_f32_32x32x16_bf16 v[2:17], v[240:243], v[134:137], v[2:17]
	s_waitcnt lgkmcnt(4)
	v_mfma_f32_32x32x16_bf16 v[82:97], v[244:247], v[134:137], v[82:97]
	s_waitcnt lgkmcnt(3)
	v_mfma_f32_32x32x16_bf16 v[2:17], v[208:211], v[138:141], v[2:17]
	s_waitcnt lgkmcnt(2)
	v_mfma_f32_32x32x16_bf16 v[82:97], v[212:215], v[138:141], v[82:97]
	s_waitcnt lgkmcnt(1)
	v_mfma_f32_32x32x16_bf16 v[2:17], v[216:219], v[142:145], v[2:17]
	s_waitcnt lgkmcnt(0)
	v_mfma_f32_32x32x16_bf16 v[82:97], v[220:223], v[142:145], v[82:97]
.LBB0_2882:
	s_andn2_b64 vcc, exec, s[62:63]
	s_cbranch_vccnz .LBB0_2884
	ds_read_b128 v[208:211], v205 offset:25600
	ds_read_b128 v[212:215], v205 offset:38400
	ds_read_b128 v[216:219], v205 offset:25632
	ds_read_b128 v[220:223], v205 offset:38432
	ds_read_b128 v[224:227], v205 offset:25664
	ds_read_b128 v[228:231], v205 offset:38464
	ds_read_b128 v[232:235], v205 offset:25696
	ds_read_b128 v[236:239], v205 offset:38496
	ds_read_b128 v[240:243], v205 offset:25728
	ds_read_b128 v[244:247], v205 offset:38528
	s_waitcnt lgkmcnt(9)
	v_mfma_f32_32x32x16_bf16 v[2:17], v[208:211], v[98:101], 0
	ds_read_b128 v[208:211], v205 offset:25760
	s_waitcnt lgkmcnt(9)
	v_mfma_f32_32x32x16_bf16 v[82:97], v[212:215], v[98:101], 0
	ds_read_b128 v[212:215], v205 offset:38560
	s_waitcnt lgkmcnt(9)
	v_mfma_f32_32x32x16_bf16 v[2:17], v[216:219], v[102:105], v[2:17]
	ds_read_b128 v[216:219], v205 offset:25792
	s_waitcnt lgkmcnt(9)
	v_mfma_f32_32x32x16_bf16 v[82:97], v[220:223], v[102:105], v[82:97]
	ds_read_b128 v[220:223], v205 offset:38592
	s_waitcnt lgkmcnt(9)
	v_mfma_f32_32x32x16_bf16 v[2:17], v[224:227], v[106:109], v[2:17]
	ds_read_b128 v[224:227], v205 offset:25824
	s_waitcnt lgkmcnt(9)
	v_mfma_f32_32x32x16_bf16 v[82:97], v[228:231], v[106:109], v[82:97]
	ds_read_b128 v[228:231], v205 offset:38624
	s_waitcnt lgkmcnt(9)
	v_mfma_f32_32x32x16_bf16 v[2:17], v[232:235], v[110:113], v[2:17]
	ds_read_b128 v[232:235], v205 offset:25856
	s_waitcnt lgkmcnt(9)
	v_mfma_f32_32x32x16_bf16 v[82:97], v[236:239], v[110:113], v[82:97]
	ds_read_b128 v[236:239], v205 offset:38656
	s_waitcnt lgkmcnt(9)
	v_mfma_f32_32x32x16_bf16 v[2:17], v[240:243], v[114:117], v[2:17]
	ds_read_b128 v[240:243], v205 offset:25888
	s_waitcnt lgkmcnt(9)
	v_mfma_f32_32x32x16_bf16 v[82:97], v[244:247], v[114:117], v[82:97]
	ds_read_b128 v[244:247], v205 offset:38688
	s_waitcnt lgkmcnt(9)
	v_mfma_f32_32x32x16_bf16 v[2:17], v[208:211], v[118:121], v[2:17]
	ds_read_b128 v[208:211], v205 offset:25920
	s_waitcnt lgkmcnt(9)
	v_mfma_f32_32x32x16_bf16 v[82:97], v[212:215], v[118:121], v[82:97]
	ds_read_b128 v[212:215], v205 offset:38720
	s_waitcnt lgkmcnt(9)
	v_mfma_f32_32x32x16_bf16 v[2:17], v[216:219], v[122:125], v[2:17]
	ds_read_b128 v[216:219], v205 offset:25952
	s_waitcnt lgkmcnt(9)
	v_mfma_f32_32x32x16_bf16 v[82:97], v[220:223], v[122:125], v[82:97]
	ds_read_b128 v[220:223], v205 offset:38752
	s_waitcnt lgkmcnt(9)
	v_mfma_f32_32x32x16_bf16 v[2:17], v[224:227], v[126:129], v[2:17]
	s_waitcnt lgkmcnt(8)
	v_mfma_f32_32x32x16_bf16 v[82:97], v[228:231], v[126:129], v[82:97]
	s_waitcnt lgkmcnt(7)
	v_mfma_f32_32x32x16_bf16 v[2:17], v[232:235], v[130:133], v[2:17]
	s_waitcnt lgkmcnt(6)
	v_mfma_f32_32x32x16_bf16 v[82:97], v[236:239], v[130:133], v[82:97]
	s_waitcnt lgkmcnt(5)
	v_mfma_f32_32x32x16_bf16 v[2:17], v[240:243], v[134:137], v[2:17]
	s_waitcnt lgkmcnt(4)
	v_mfma_f32_32x32x16_bf16 v[82:97], v[244:247], v[134:137], v[82:97]
	s_waitcnt lgkmcnt(3)
	v_mfma_f32_32x32x16_bf16 v[2:17], v[208:211], v[138:141], v[2:17]
	s_waitcnt lgkmcnt(2)
	v_mfma_f32_32x32x16_bf16 v[82:97], v[212:215], v[138:141], v[82:97]
	s_waitcnt lgkmcnt(1)
	v_mfma_f32_32x32x16_bf16 v[2:17], v[216:219], v[142:145], v[2:17]
	s_waitcnt lgkmcnt(0)
	v_mfma_f32_32x32x16_bf16 v[82:97], v[220:223], v[142:145], v[82:97]
